# rebalance deferred weight transposes over both idle slots; first 128 workgroups take their sample-chunk attention unit before joining the prompt block queue
# baseline (speedup 1.0000x reference)
; __global__ void __launch_bounds__(512, 2) fox_fwd(Args args) {
;     ...
;         const int gw = bx * 8 + wave, NGW = G * 8;
;         constexpr int I_GU = (DM / 64) * (DFF / 32), I_DN = (DFF / 64) * (DM / 32), I_INA = (DM / 64) * (3 * FOXW / 32), I_INP = (DM / 64) * (POOLW / 32), I_O = (DM / 64) * (DM / 32), I_PL = 4 * (256 / 64) * (256 / 32);
;         constexpr int NITEMS = 4 * I_GU + 2 * I_DN + I_INA + I_INP + I_O + I_PL;
;         for (int it = gw; it < NITEMS; it += NGW) {
;             int r = it;
;             if (r < 4 * I_GU) {
;                 const int which = r / I_GU; r -= which * I_GU; const int nblk = DFF / 32, kb = r / nblk, nb = r % nblk, n0 = 32 * nb;
;                 const float* W = A_->in[which == 0 ? 7 : which == 1 ? 8 : which == 2 ? 17 : 18];
;                 bf16_t* WT = which < 2 ? Wgu1 : Wgu2; const int drow = (n0 >> 7) * 256 + (which & 1) * 128 + (n0 & 127);
;                 transpose_item(W + n0, DFF, WT, DM, drow, 64 * kb, scr, lane, which < 2 ? nullptr : A_->in[16]); continue; }
;             r -= 4 * I_GU;
;             if (r < 2 * I_DN) { const int which = r / I_DN; r -= which * I_DN; const int nblk = DM / 32, kb = r / nblk, nb = r % nblk;
;                 transpose_item(A_->in[which == 0 ? 9 : 19] + 32 * nb, DM, which == 0 ? Wd1 : Wd2, DFF, 32 * nb, 64 * kb, scr, lane); continue; }
;             r -= 2 * I_DN;
;             if (r < I_INA) { const int nblk = 3 * FOXW / 32, kb = r / nblk, nb = r % nblk; transpose_item(A_->in[11] + 32 * nb, INW, Win, DM, 32 * nb, 64 * kb, scr, lane, A_->in[10]); continue; }
;             r -= I_INA;
;             if (r < I_INP) { const int nblk = POOLW / 32, kb = r / nblk, nb = r % nblk; transpose_item(A_->in[11] + 3 * FOXW + NH + 32 * nb, INW, Win, DM, 3 * FOXW + 32 * nb, 64 * kb, scr, lane, A_->in[10]); continue; }
;             r -= I_INP;
;             if (r < I_O) { const int nblk = DM / 32, kb = r / nblk, nb = r % nblk;
;                 if (kb < 16) transpose_item(A_->in[15] + 32 * nb, DM, Wo, DM, 32 * nb, 64 * kb, scr, lane);
;                 else transpose_item(A_->in[15] + (size_t)FOXW * DM + 32 * nb, DM, (bf16_t*)(ws + WS_D), FOXW, 32 * nb, 64 * kb - FOXW, scr, lane);
;                 continue; }
;             r -= I_O;
;             { }
;         }
.Lp0_m1:
	s_cmp_eq_u32 s99, 1
	s_cbranch_scc0 .Lp0_m2
	s_add_u32 s50, s16, 0x5540
	s_movk_i32 s18, 0x540
	s_mov_b32 s100, 0x83ff
	s_branch .Lp0_strides
.Lp0_m2:
	s_movk_i32 s18, 0x600
	s_cmp_eq_u32 s99, 2
	s_cbranch_scc0 .Lp0_m3
	s_add_u32 s50, s16, 0x2a00
	s_movk_i32 s100, 0x57ff
	s_branch .Lp0_strides
.Lp0_m3:
	s_add_u32 s50, s16, 0x8200
	s_mov_b32 s100, 0x9bff

; __device__ __forceinline__ unsigned f2bf(float f) { unsigned u = __builtin_bit_cast(unsigned, f); return (u + 0x7fffu + ((u >> 16) & 1u)) >> 16; }
; __global__ void __launch_bounds__(512, 2) fox_fwd(Args args) {
;     ...
;         for (int i = bx * 512 + tid; i < NH * DM; i += G * 512) { const int j = i / DM, k = i % DM; Win[(size_t)(4 * FOXW + j) * DM + k] = (bf16_t)f2bf(A_->in[11][(size_t)k * INW + 3 * FOXW + j] * A_->in[10][k]); }
.LBB0_96:
	s_cmp_eq_u32 s99, 1
	s_cbranch_scc1 .Lp0_ret1
	s_cmp_eq_u32 s99, 2
	s_cbranch_scc1 .Lp0_ret2
	s_cmp_eq_u32 s99, 3
	s_cbranch_scc1 .Lp0_ret3
	v_lshl_add_u32 v4, s2, 9, v33
	s_movk_i32 s1, 0x4000
	v_cmp_gt_i32_e32 vcc, s1, v4
	s_and_saveexec_b64 s[26:27], vcc
	s_cbranch_execz .LBB0_104
	s_lshl_b32 s0, s48, 9
	v_cvt_f32_u32_e32 v0, s0
	v_add_u32_e32 v5, s0, v4
	v_mov_b32_e32 v1, s0
	v_cmp_gt_i32_e32 vcc, s1, v5
	v_rcp_iflag_f32_e32 v0, v0
	s_sub_i32 s3, 0, s0
	v_max_i32_e32 v2, 0x4000, v5
	v_addc_co_u32_e64 v1, s[4:5], v4, v1, vcc
	v_mul_f32_e32 v0, 0x4f7ffffe, v0
	v_cvt_u32_f32_e32 v0, v0
	v_sub_u32_e32 v1, v2, v1
	s_load_dwordx4 s[12:15], s[22:23], 0x50
	s_mov_b64 s[28:29], -1
	v_mul_lo_u32 v2, s3, v0
	v_mul_hi_u32 v2, v0, v2
	v_add_u32_e32 v0, v0, v2
	v_mul_hi_u32 v0, v1, v0
	v_mul_lo_u32 v2, v0, s0
	v_sub_u32_e32 v1, v1, v2
	v_add_u32_e32 v2, 1, v0
	v_cmp_le_u32_e64 s[4:5], s0, v1
	s_nop 1
	v_cndmask_b32_e64 v0, v0, v2, s[4:5]
	v_subrev_u32_e32 v2, s0, v1
	v_cndmask_b32_e64 v1, v1, v2, s[4:5]
	v_add_u32_e32 v2, 1, v0
	v_cmp_le_u32_e64 s[4:5], s0, v1
	s_nop 1
	v_cndmask_b32_e64 v0, v0, v2, s[4:5]
	v_addc_co_u32_e32 v6, vcc, 1, v0, vcc
	v_cmp_lt_u32_e32 vcc, 1, v6
	v_mov_b32_e32 v0, v4
	s_and_saveexec_b64 s[4:5], vcc
	s_cbranch_execz .LBB0_101
	v_and_b32_e32 v7, -2, v6
	s_lshl_b32 s1, s48, 10
	s_mov_b32 s3, s1
	s_mov_b64 s[28:29], 0
	s_movk_i32 s17, 0x4020
	s_waitcnt lgkmcnt(0)
	v_mov_b64_e32 v[0:1], s[14:15]
	s_movk_i32 s19, 0x3000
	s_movk_i32 s30, 0x7fff
	s_mov_b32 s31, 0x1000000
	v_mov_b32_e32 v8, 1
	v_mov_b32_e32 v9, v7
	v_mov_b64_e32 v[2:3], v[4:5]

; #define SEAM(k) do { if (IN(k) && IN((k) + 1)) { unsigned* bar_ = (unsigned*)kargs()->ws; xcd_barrier(bar_, (volatile LAS unsigned*)((PG8_LAS unsigned char*)lds + LDS_BARST)); } } while (0)
; __global__ void __launch_bounds__(512, 2) fox_fwd(Args args) {
;     ...
;     if (IN(2)) { PTRS TIDS pg8::Gemm g{HB, Wd1, MTOT, DM, DFF, DFF, 0}; pg8::StaticOrder S; S.init(MTOT, DM, DFF, G, bx, 0, SPL, SPC);
;         pg8::EpiRes E{x_prompt, x_sample, nullptr, 0.5f, ABUF, rowss1}; pg8::gemm_phase(lds3, g, S, E); }
;     SEAM(2);
.Lp0_ret2:
	v_readlane_b32 s54, v250, 3
	v_readlane_b32 s55, v250, 4
	s_mov_b32 s99, 3
	s_nop 3
	s_branch .Lp0_reenter

; #define GRAB(dst) do { if (tid == 0) *nl = (int)__hip_atomic_fetch_add(qctr, 1u, __ATOMIC_RELAXED, __HIP_MEMORY_SCOPE_AGENT); __syncthreads(); dst = __builtin_amdgcn_readfirstlane(*nl); __syncthreads(); } while (0)
; __global__ void __launch_bounds__(512, 2) fox_fwd(Args args) {
;     ...
;             fox::Seam S; unsigned* qctr = (unsigned*)(ws + WS_QUEUE); const float* QN = (const float*)(ws + WS_QN); const float* KN = (const float*)(ws + WS_KN);
;             int* nl = (int*)((char*)lds + fox::LDS_BIAS - 32);
;             auto mkref = [&](int n) { const int bh = n & 31, qb = 31 - (n >> 5), b = bh >> 3, h = bh & 7;
;                 fox::BlockRef r; r.K = Kb + (size_t)bh * SEQ * HD; r.O = MIX + ((size_t)b * SEQ + (size_t)qb * 256) * DM + h * HD; r.C = Cp + (size_t)bh * SEQ; r.P0 = qb * 256;
;                 r.nrm = 1.02f * fox::SCALE * sqrtf(QN[bh * 32 + qb] * KN[bh]); return r; };
;     ...
;             int n; GRAB(n);
;             if (n < NB * NH * 32) {
;     ...
;         if (P5_PARTS & 2) for (;;) { int* nl2 = (int*)((char*)lds + 65536); unsigned* sctr = (unsigned*)(ws + WS_QUEUE) + 16;
;             __syncthreads(); if (tid == 0) *nl2 = (int)__hip_atomic_fetch_add(sctr, 1u, __ATOMIC_RELAXED, __HIP_MEMORY_SCOPE_AGENT); __syncthreads(); const int u = __builtin_amdgcn_readfirstlane(*nl2); __syncthreads(); if (u >= SBATCH * NH) break;
;             const int b = u >> 3, h = u & 7;
;             fox::sample_unit(b, h, A_->in[2], A_->in[3], A_->in[4], out + O_KS, out + O_VS, out + O_LFS, Qb + (size_t)MP * FOXW, MIX + (size_t)MP * DM, (char*)lds);
.Lp5_top:
	s_load_dwordx4 s[12:15], s[54:55], 0xa8
	v_mov_b32_e32 v0, v182
	s_waitcnt lgkmcnt(0)
	s_add_u32 s10, s14, 0x5000
	s_addc_u32 s11, s15, 0
	v_cmp_eq_u32_e64 s[4:5], 0, v0
	s_cmp_lg_u32 s99, 0
	s_cbranch_scc1 .Lp5_prompt
	s_cmp_lt_u32 s2, 0x80
	s_cbranch_scc0 .Lp5_prompt
	s_mov_b32 s99, 5
	s_mov_b32 s57, 0
	s_branch .LBB0_1298
.Lp5_prompt:
	s_and_saveexec_b64 s[6:7], s[4:5]
	s_cbranch_execz .LBB0_1113
	s_mov_b64 s[16:17], exec
	v_mbcnt_lo_u32_b32 v0, s16, 0
	v_mbcnt_hi_u32_b32 v0, s17, v0
	v_cmp_eq_u32_e32 vcc, 0, v0
	s_and_saveexec_b64 s[8:9], vcc
	s_cbranch_execz .LBB0_1112
	s_bcnt1_i32_b64 s0, s[16:17]
	v_mov_b32_e32 v1, 0
	v_mov_b32_e32 v2, s0
	global_atomic_add v1, v1, v2, s[10:11] sc0

; __global__ void __launch_bounds__(512, 2) fox_fwd(Args args) {
;     ...
;             asm volatile("s_waitcnt vmcnt(0)" ::: "memory"); __syncthreads();
;         }
;         if (P5_PARTS & 2) for (;;) { int* nl2 = (int*)((char*)lds + 65536); unsigned* sctr = (unsigned*)(ws + WS_QUEUE) + 16;
;             __syncthreads(); if (tid == 0) *nl2 = (int)__hip_atomic_fetch_add(sctr, 1u, __ATOMIC_RELAXED, __HIP_MEMORY_SCOPE_AGENT); __syncthreads(); const int u = __builtin_amdgcn_readfirstlane(*nl2); __syncthreads(); if (u >= SBATCH * NH) break;
;             const int b = u >> 3, h = u & 7;
;             fox::sample_unit(b, h, A_->in[2], A_->in[3], A_->in[4], out + O_KS, out + O_VS, out + O_LFS, Qb + (size_t)MP * FOXW, MIX + (size_t)MP * DM, (char*)lds);
;         }
;         __syncthreads();
;     }
.LBB0_1391:
	v_readlane_b32 s54, v250, 3
	v_readlane_b32 s44, v250, 5
	v_readlane_b32 s55, v250, 4
	v_readlane_b32 s45, v250, 6
	s_cmp_eq_u32 s99, 5
	s_cbranch_scc0 .Lp5_done
	s_mov_b32 s99, 6
	s_nop 3
	s_branch .Lp5_top
.Lp5_done:
	s_mov_b32 s99, 0
	s_barrier
